# grid barrier between phase 18 (layer-0 FFN2-down GEMM) and phase 19 (layer-1 weight conversion, reads only kernel inputs) removed
# speedup vs baseline: 1.0082x; 1.0029x over previous
my_tolatch:
	s_getpc_b64 s[98:99]

.LBB0_804:
	s_cmp_eq_u32 s22, 18
	s_cbranch_scc1 my_tolatch
	s_waitcnt vmcnt(0)
	s_waitcnt vmcnt(0) lgkmcnt(0)
	s_barrier
	s_mov_b64 s[4:5], exec
	v_readlane_b32 s10, v252, 2
	v_readlane_b32 s11, v252, 3
	s_and_b64 s[10:11], s[4:5], s[10:11]
	s_mov_b64 exec, s[10:11]
	s_cbranch_execz .LBB0_858
	v_readlane_b32 s6, v255, 6
	s_waitcnt vmcnt(0) expcnt(0) lgkmcnt(0)
	s_nop 0
	v_mov_b32_e32 v0, s6
	ds_read_b32 v2, v0
	v_readlane_b32 s6, v255, 7
	s_waitcnt lgkmcnt(0)
	v_cmp_ne_u32_e32 vcc, 0, v2
	v_mov_b32_e32 v0, s6
	ds_read_b32 v0, v0
	s_cbranch_vccnz .LBB0_822
	s_mov_b32 s6, 1
	s_branch .LBB0_809
